# combo3g + start stagger (4 CU groups, ~4us steps) in 2-unit GEMM phases 6,9,13,16 to desynchronize epilogue bursts
# baseline (speedup 1.0000x reference)
; #define SEAM(k) do { if (IN((k) + 1)) grid.sync(); } while (0)
; #define SEAM(k) do { if (hi > (k) + 1) { if (lo > hi) grid.sync(); xcd_barrier(bar); } } while (0)
; __global__ void __launch_bounds__(NTHR, 2) hybrid_fwd(Args args) {
;     ...
;     if (IN(6)) { BODY6; if (PROBE_ID == 106) BODY6; SEAM(6); }
.LBB0_584:
	s_cmp_lt_i32 s80, 7
	s_cselect_b64 s[0:1], -1, 0
	s_cmp_gt_i32 s81, 6
	s_cselect_b64 s[2:3], -1, 0
	s_and_b64 s[0:1], s[0:1], s[2:3]
	s_andn2_b64 vcc, exec, s[0:1]
	s_cbranch_vccnz .LBB0_681
	s_bfe_u32 s98, s96, 0x20003
	s_mul_i32 s98, s98, 4
	s_cmp_eq_u32 s98, 0
	s_cbranch_scc1 .Lstg_done6
.Lstg_loop6:
	s_sleep 32
	s_sub_u32 s98, s98, 1
	s_cmp_lg_u32 s98, 0
	s_cbranch_scc1 .Lstg_loop6
.Lstg_done6:
	s_mov_b32 s0, 0
	s_ashr_i32 s1, s0, 31
	s_lshl_b64 s[0:1], s[0:1], 3
	s_add_u32 s4, s74, s0
	s_addc_u32 s5, s75, s1
	v_mov_b32_e32 v10, v0
	s_cmpk_lt_i32 s96, 0x200
	s_cselect_b64 s[6:7], -1, 0
	s_cmpk_gt_i32 s96, 0x1ff
	v_readfirstlane_b32 s20, v10
	s_cbranch_scc0 .LBB0_588
	s_load_dwordx2 s[4:5], s[4:5], 0x0
	s_andn2_b64 vcc, exec, s[6:7]
	s_cbranch_vccz .LBB0_593

.LBB0_882:
	s_cmp_lt_i32 s80, 10
	s_cselect_b64 s[0:1], -1, 0
	s_cmp_gt_i32 s81, 9
	s_cselect_b64 s[2:3], -1, 0
	s_and_b64 s[0:1], s[0:1], s[2:3]
	s_andn2_b64 vcc, exec, s[0:1]
	s_cbranch_vccnz .LBB0_979
	s_bfe_u32 s98, s96, 0x20003
	s_mul_i32 s98, s98, 4
	s_cmp_eq_u32 s98, 0
	s_cbranch_scc1 .Lstg_done9

.Lstg_done9:
	v_mov_b32_e32 v10, v0
	s_cmpk_lt_i32 s96, 0x200
	s_cselect_b64 s[6:7], -1, 0
	s_cmpk_gt_i32 s96, 0x1ff
	v_readfirstlane_b32 s0, v10
	s_cbranch_scc0 .LBB0_886
	s_andn2_b64 vcc, exec, s[6:7]
	s_cbranch_vccz .LBB0_891

; #define SEAM(k) do { if (IN((k) + 1)) grid.sync(); } while (0)
; #define GEMM_STD(Aptr, Bptr, ldk, Ncols, EpiT, Eobj) do { pg8::Gemm g_{(const bf16*)(Aptr), (const bf16*)(Bptr), (ldk), (ldk), (ldk), 0, 0}; pg8::StaticOrder S_; S_.init(M, (Ncols), (int)gridDim.x, (int)blockIdx.x); \
;         pg8::gemm_phase<EpiT, pg8::StaticOrder, true, true>((LAS unsigned char*)lds, g_, S_, Eobj); } while (0)
; #define SEAM(k) do { if (hi > (k) + 1) { if (lo > hi) grid.sync(); xcd_barrier(bar); } } while (0)
; __global__ void __launch_bounds__(NTHR, 2) hybrid_fwd(Args args) {
;     ...
;     if (IN(13)) { EpiRes<false> E{WSB(WS_MIX), WSB(WS_MIX), SSQ(4)}; GEMM_STD(WSB(WS_PP), WSB(WS_WO), 1024, 1024, EpiRes<false>, E); SEAM(13); }
.LBB0_1446:
	s_cmp_lt_i32 s80, 14
	s_cselect_b64 s[0:1], -1, 0
	s_cmp_gt_i32 s81, 13
	s_cselect_b64 s[2:3], -1, 0
	s_and_b64 s[0:1], s[0:1], s[2:3]
	s_andn2_b64 vcc, exec, s[0:1]
	s_cbranch_vccnz .LBB0_1543
	s_bfe_u32 s98, s96, 0x20003
	s_mul_i32 s98, s98, 4
	s_cmp_eq_u32 s98, 0
	s_cbranch_scc1 .Lstg_done13

; #define SEAM(k) do { if (IN((k) + 1)) grid.sync(); } while (0)
; #define GEMM_STD(Aptr, Bptr, ldk, Ncols, EpiT, Eobj) do { pg8::Gemm g_{(const bf16*)(Aptr), (const bf16*)(Bptr), (ldk), (ldk), (ldk), 0, 0}; pg8::StaticOrder S_; S_.init(M, (Ncols), (int)gridDim.x, (int)blockIdx.x); \
;         pg8::gemm_phase<EpiT, pg8::StaticOrder, true, true>((LAS unsigned char*)lds, g_, S_, Eobj); } while (0)
; #define SEAM(k) do { if (hi > (k) + 1) { if (lo > hi) grid.sync(); xcd_barrier(bar); } } while (0)
; __global__ void __launch_bounds__(NTHR, 2) hybrid_fwd(Args args) {
;     ...
;     if (IN(13)) { EpiRes<false> E{WSB(WS_MIX), WSB(WS_MIX), SSQ(4)}; GEMM_STD(WSB(WS_PP), WSB(WS_WO), 1024, 1024, EpiRes<false>, E); SEAM(13); }
.Lstg_done13:
	v_mov_b32_e32 v10, v0
	s_cmpk_lt_i32 s96, 0x200
	s_cselect_b64 s[6:7], -1, 0
	s_cmpk_gt_i32 s96, 0x1ff
	v_readfirstlane_b32 s8, v10
	s_cbranch_scc0 .LBB0_1450
	s_andn2_b64 vcc, exec, s[6:7]
	s_cbranch_vccz .LBB0_1455

; __global__ void __launch_bounds__(NTHR, 2) hybrid_fwd(Args args) {
;     ...
;     FFN_PLE(1, 14, 4, WS_MIX, WS_HN)
.LBB0_1744:
	s_cmp_lt_i32 s80, 17
	s_cselect_b64 s[0:1], -1, 0
	s_cmp_gt_i32 s81, 16
	s_cselect_b64 s[2:3], -1, 0
	s_and_b64 s[0:1], s[0:1], s[2:3]
	s_andn2_b64 vcc, exec, s[0:1]
	s_cbranch_vccnz .LBB0_1841
	s_bfe_u32 s98, s96, 0x20003
	s_mul_i32 s98, s98, 4
	s_cmp_eq_u32 s98, 0
	s_cbranch_scc1 .Lstg_done16
